# RMSNorm: 9 consecutive rows per wave, norm_g / shift / scale kept in registers (was 24 parameter loads per row)
# baseline (speedup 1.0000x reference)
.LBB0_84:
	v_readfirstlane_b32 s4, v34
	v_readlane_b32 s98, v250, 21
	v_readlane_b32 s99, v250, 22
	v_lshrrev_b32_e32 v81, 1, v50
	s_nop 3
	s_mul_i32 s4, s4, 9
	s_add_i32 s83, s4, 9
	s_min_u32 s83, s83, 0x4800
	s_mov_b32 s78, -1
	global_load_dwordx4 v[94:97], v[36:37], off
	global_load_dwordx4 v[98:101], v[36:37], off offset:1024
	global_load_dwordx4 v[102:105], v[36:37], off offset:2048
	global_load_dwordx4 v[106:109], v[36:37], off offset:3072
	global_load_dwordx4 v[110:113], v[38:39], off
	global_load_dwordx4 v[114:117], v[38:39], off offset:1024
	global_load_dwordx4 v[118:121], v[38:39], off offset:2048
	global_load_dwordx4 v[122:125], v[38:39], off offset:3072
	s_lshl_b32 s5, s4, 13
	s_add_u32 s8, s98, s5
	s_addc_u32 s9, s99, 0
	s_sub_i32 s5, s4, 0x4000
	s_lshl_b32 s5, s5, 13
	s_add_u32 s35, s48, s5
	s_addc_u32 s41, s49, 0
	s_cmp_lt_u32 s4, 0x4000
	s_cselect_b32 s8, s8, s35
	s_cselect_b32 s9, s9, s41
	global_load_dwordx4 v[206:209], v50, s[8:9]
	global_load_dwordx4 v[210:213], v50, s[8:9] offset:1024
	global_load_dwordx4 v[214:217], v50, s[8:9] offset:2048
	global_load_dwordx4 v[218:221], v50, s[8:9] offset:3072
	global_load_dwordx4 v[222:225], v58, s[8:9]
	global_load_dwordx4 v[226:229], v58, s[8:9] offset:1024
	global_load_dwordx4 v[242:245], v58, s[8:9] offset:2048
	global_load_dwordx4 v[246:249], v58, s[8:9] offset:3072
	s_waitcnt vmcnt(0)
.Lnorm_loop:
	s_lshl_b32 s5, s4, 12
	s_add_u32 s100, s96, s5
	s_addc_u32 s101, s97, 0
	s_waitcnt vmcnt(8)
	v_mov_b32_e32 v30, v206
	v_mov_b32_e32 v31, v207
	v_mov_b32_e32 v32, v208
	v_mov_b32_e32 v33, v209
	v_mov_b32_e32 v26, v210
	v_mov_b32_e32 v27, v211
	v_mov_b32_e32 v28, v212
	v_mov_b32_e32 v29, v213
	v_mov_b32_e32 v22, v214
	v_mov_b32_e32 v23, v215
	v_mov_b32_e32 v24, v216
	v_mov_b32_e32 v25, v217
	v_mov_b32_e32 v18, v218
	v_mov_b32_e32 v19, v219
	v_mov_b32_e32 v20, v220
	v_mov_b32_e32 v21, v221
	v_mov_b32_e32 v14, v222
	v_mov_b32_e32 v15, v223
	v_mov_b32_e32 v16, v224
	v_mov_b32_e32 v17, v225
	v_mov_b32_e32 v6, v226
	v_mov_b32_e32 v7, v227
	v_mov_b32_e32 v8, v228
	v_mov_b32_e32 v9, v229
	v_mov_b32_e32 v82, v242
	v_mov_b32_e32 v83, v243
	v_mov_b32_e32 v84, v244
	v_mov_b32_e32 v85, v245
	v_mov_b32_e32 v86, v246
	v_mov_b32_e32 v87, v247
	v_mov_b32_e32 v88, v248
	v_mov_b32_e32 v89, v249
	s_add_i32 s32, s4, 1
	s_cmp_ge_u32 s32, s83
	s_cselect_b32 s5, s4, s32
	s_lshl_b32 s35, s5, 13
	s_add_u32 s8, s98, s35
	s_addc_u32 s9, s99, 0
	s_sub_i32 s35, s5, 0x4000
	s_lshl_b32 s35, s35, 13
	s_add_u32 s35, s48, s35
	s_addc_u32 s41, s49, 0
	s_cmp_lt_u32 s5, 0x4000
	s_cselect_b32 s8, s8, s35
	s_cselect_b32 s9, s9, s41
	global_load_dwordx4 v[206:209], v50, s[8:9]
	global_load_dwordx4 v[210:213], v50, s[8:9] offset:1024
	global_load_dwordx4 v[214:217], v50, s[8:9] offset:2048
	global_load_dwordx4 v[218:221], v50, s[8:9] offset:3072
	global_load_dwordx4 v[222:225], v58, s[8:9]
	global_load_dwordx4 v[226:229], v58, s[8:9] offset:1024
	global_load_dwordx4 v[242:245], v58, s[8:9] offset:2048
	global_load_dwordx4 v[246:249], v58, s[8:9] offset:3072
	s_min_u32 s5, s4, 0x4000
	s_lshr_b32 s5, s5, 11
	s_cmp_eq_u32 s5, s78
	s_cbranch_scc1 .Lnorm_params_ok
	s_mov_b32 s78, s5
	s_mul_i32 s5, s5, 0x6000
	s_add_u32 s10, s6, s5
	s_addc_u32 s11, s7, 0
	s_add_u32 s86, s10, 0x2000
	s_addc_u32 s87, s11, 0
	global_load_dwordx4 v[126:129], v50, s[10:11]
	global_load_dwordx4 v[158:161], v50, s[86:87]
	global_load_dwordx4 v[130:133], v50, s[10:11] offset:1024
	global_load_dwordx4 v[162:165], v50, s[86:87] offset:1024
	global_load_dwordx4 v[134:137], v50, s[10:11] offset:2048
	global_load_dwordx4 v[166:169], v50, s[86:87] offset:2048
	global_load_dwordx4 v[138:141], v50, s[10:11] offset:3072
	global_load_dwordx4 v[170:173], v50, s[86:87] offset:3072
	global_load_dwordx4 v[142:145], v58, s[10:11]
	global_load_dwordx4 v[174:177], v58, s[86:87]
	global_load_dwordx4 v[146:149], v58, s[10:11] offset:1024
	global_load_dwordx4 v[178:181], v58, s[86:87] offset:1024
	global_load_dwordx4 v[150:153], v58, s[10:11] offset:2048
	global_load_dwordx4 v[182:185], v58, s[86:87] offset:2048
	global_load_dwordx4 v[154:157], v58, s[10:11] offset:3072
	global_load_dwordx4 v[186:189], v58, s[86:87] offset:3072
	s_waitcnt vmcnt(0)
.Lnorm_params_ok:
	v_mul_f32_e32 v4, v31, v31
	v_mul_f32_e32 v5, v27, v27
	v_fmac_f32_e32 v4, v30, v30
	v_fmac_f32_e32 v5, v26, v26
	v_fmac_f32_e32 v4, v32, v32
	v_fmac_f32_e32 v5, v28, v28
	v_fmac_f32_e32 v4, v33, v33
	v_fmac_f32_e32 v5, v29, v29
	v_add_f32_e32 v4, v4, v5
	v_mul_f32_e32 v5, v23, v23
	v_fmac_f32_e32 v5, v22, v22
	v_fmac_f32_e32 v5, v24, v24
	v_fmac_f32_e32 v5, v25, v25
	v_add_f32_e32 v4, v4, v5
	v_mul_f32_e32 v5, v19, v19
	v_fmac_f32_e32 v5, v18, v18
	v_fmac_f32_e32 v5, v20, v20
	v_fmac_f32_e32 v5, v21, v21
	v_mov_b32_e32 v10, v15
	v_mov_b32_e32 v11, v7
	v_add_f32_e32 v12, v4, v5
	v_mov_b32_e32 v4, v14
	v_mov_b32_e32 v5, v6
	v_pk_mul_f32 v[10:11], v[10:11], v[10:11]
	s_nop 0
	v_pk_fma_f32 v[4:5], v[4:5], v[4:5], v[10:11]
	v_mov_b32_e32 v10, v16
	v_mov_b32_e32 v11, v8
	v_pk_fma_f32 v[4:5], v[10:11], v[10:11], v[4:5]
	v_mov_b32_e32 v10, v17
	v_mov_b32_e32 v11, v9
	v_pk_fma_f32 v[4:5], v[10:11], v[10:11], v[4:5]
	s_nop 0
	v_add_f32_e32 v4, v12, v4
	v_add_f32_e32 v66, v4, v5
	v_mov_b32_e32 v74, v83
	v_mov_b32_e32 v75, v87
	v_mov_b32_e32 v70, v82
	v_mov_b32_e32 v71, v86
	v_pk_mul_f32 v[74:75], v[74:75], v[74:75]
	s_nop 0
	v_pk_fma_f32 v[70:71], v[70:71], v[70:71], v[74:75]
	v_mov_b32_e32 v74, v84
	v_mov_b32_e32 v75, v88
	v_pk_fma_f32 v[70:71], v[74:75], v[74:75], v[70:71]
	v_mov_b32_e32 v74, v85
	v_mov_b32_e32 v75, v89
	v_pk_fma_f32 v[70:71], v[74:75], v[74:75], v[70:71]
	s_nop 0
	v_add_f32_e32 v66, v66, v70
	v_add_f32_e32 v66, v66, v71
	ds_bpermute_b32 v70, v67, v66
	s_waitcnt lgkmcnt(0)
	v_add_f32_e32 v66, v66, v70
	ds_bpermute_b32 v70, v76, v66
	s_waitcnt lgkmcnt(0)
	v_add_f32_e32 v66, v66, v70
	ds_bpermute_b32 v70, v77, v66
	s_waitcnt lgkmcnt(0)
	v_add_f32_e32 v66, v66, v70
	ds_bpermute_b32 v70, v78, v66
	s_waitcnt lgkmcnt(0)
	v_add_f32_e32 v66, v66, v70
	ds_bpermute_b32 v70, v79, v66
	s_waitcnt lgkmcnt(0)
	v_add_f32_e32 v66, v66, v70
	ds_bpermute_b32 v70, v80, v66
	s_waitcnt lgkmcnt(0)
	v_add_f32_e32 v66, v66, v70
	v_fmamk_f32 v66, v66, 0x3a000000, v230
	v_cmp_gt_f32_e32 vcc, s70, v66
	v_mul_f32_e32 v70, 0x4b800000, v66
	s_nop 0
	v_cndmask_b32_e32 v66, v66, v70, vcc
	v_rsq_f32_e32 v66, v66
	s_nop 0
	v_mul_f32_e32 v70, 0x45800000, v66
	v_cndmask_b32_e32 v66, v66, v70, vcc
	v_pk_mul_f32 v[30:31], v[30:31], v[66:67] op_sel_hi:[1,0]
	v_pk_mul_f32 v[32:33], v[32:33], v[66:67] op_sel_hi:[1,0]
	v_pk_mul_f32 v[26:27], v[26:27], v[66:67] op_sel_hi:[1,0]
	v_pk_mul_f32 v[28:29], v[28:29], v[66:67] op_sel_hi:[1,0]
	v_pk_mul_f32 v[22:23], v[22:23], v[66:67] op_sel_hi:[1,0]
	v_pk_mul_f32 v[24:25], v[24:25], v[66:67] op_sel_hi:[1,0]
	v_pk_mul_f32 v[18:19], v[18:19], v[66:67] op_sel_hi:[1,0]
	v_pk_mul_f32 v[20:21], v[20:21], v[66:67] op_sel_hi:[1,0]
	v_pk_mul_f32 v[14:15], v[14:15], v[66:67] op_sel_hi:[1,0]
	v_pk_mul_f32 v[16:17], v[16:17], v[66:67] op_sel_hi:[1,0]
	v_pk_mul_f32 v[6:7], v[6:7], v[66:67] op_sel_hi:[1,0]
	v_pk_mul_f32 v[8:9], v[8:9], v[66:67] op_sel_hi:[1,0]
	v_pk_mul_f32 v[82:83], v[82:83], v[66:67] op_sel_hi:[1,0]
	v_pk_mul_f32 v[84:85], v[84:85], v[66:67] op_sel_hi:[1,0]
	v_pk_mul_f32 v[86:87], v[86:87], v[66:67] op_sel_hi:[1,0]
	v_pk_mul_f32 v[88:89], v[88:89], v[66:67] op_sel_hi:[1,0]
	v_pk_mul_f32 v[30:31], v[94:95], v[30:31]
	v_pk_mul_f32 v[32:33], v[96:97], v[32:33]
	v_pk_add_f32 v[4:5], v[158:159], 1.0 op_sel_hi:[1,0]
	v_pk_add_f32 v[10:11], v[160:161], 1.0 op_sel_hi:[1,0]
	v_pk_fma_f32 v[30:31], v[4:5], v[30:31], v[126:127]
	v_pk_fma_f32 v[32:33], v[10:11], v[32:33], v[128:129]
	v_cvt_pk_bf16_f32 v12, v30, v31
	v_cvt_pk_bf16_f32 v13, v32, v33
	global_store_dwordx2 v81, v[12:13], s[100:101]
	v_pk_mul_f32 v[26:27], v[98:99], v[26:27]
	v_pk_mul_f32 v[28:29], v[100:101], v[28:29]
	v_pk_add_f32 v[4:5], v[162:163], 1.0 op_sel_hi:[1,0]
	v_pk_add_f32 v[10:11], v[164:165], 1.0 op_sel_hi:[1,0]
	v_pk_fma_f32 v[26:27], v[4:5], v[26:27], v[130:131]
	v_pk_fma_f32 v[28:29], v[10:11], v[28:29], v[132:133]
	v_cvt_pk_bf16_f32 v12, v26, v27
	v_cvt_pk_bf16_f32 v13, v28, v29
	global_store_dwordx2 v81, v[12:13], s[100:101] offset:512
	v_pk_mul_f32 v[22:23], v[102:103], v[22:23]
	v_pk_mul_f32 v[24:25], v[104:105], v[24:25]
	v_pk_add_f32 v[4:5], v[166:167], 1.0 op_sel_hi:[1,0]
	v_pk_add_f32 v[10:11], v[168:169], 1.0 op_sel_hi:[1,0]
	v_pk_fma_f32 v[22:23], v[4:5], v[22:23], v[134:135]
	v_pk_fma_f32 v[24:25], v[10:11], v[24:25], v[136:137]
	v_cvt_pk_bf16_f32 v12, v22, v23
	v_cvt_pk_bf16_f32 v13, v24, v25
	global_store_dwordx2 v81, v[12:13], s[100:101] offset:1024
	v_pk_mul_f32 v[18:19], v[106:107], v[18:19]
	v_pk_mul_f32 v[20:21], v[108:109], v[20:21]
	v_pk_add_f32 v[4:5], v[170:171], 1.0 op_sel_hi:[1,0]
	v_pk_add_f32 v[10:11], v[172:173], 1.0 op_sel_hi:[1,0]
	v_pk_fma_f32 v[18:19], v[4:5], v[18:19], v[138:139]
	v_pk_fma_f32 v[20:21], v[10:11], v[20:21], v[140:141]
	v_cvt_pk_bf16_f32 v12, v18, v19
	v_cvt_pk_bf16_f32 v13, v20, v21
	global_store_dwordx2 v81, v[12:13], s[100:101] offset:1536
	v_pk_mul_f32 v[14:15], v[110:111], v[14:15]
	v_pk_mul_f32 v[16:17], v[112:113], v[16:17]
	v_pk_add_f32 v[4:5], v[174:175], 1.0 op_sel_hi:[1,0]
	v_pk_add_f32 v[10:11], v[176:177], 1.0 op_sel_hi:[1,0]
	v_pk_fma_f32 v[14:15], v[4:5], v[14:15], v[142:143]
	v_pk_fma_f32 v[16:17], v[10:11], v[16:17], v[144:145]
	v_cvt_pk_bf16_f32 v12, v14, v15
	v_cvt_pk_bf16_f32 v13, v16, v17
	global_store_dwordx2 v81, v[12:13], s[100:101] offset:2048
	v_pk_mul_f32 v[6:7], v[114:115], v[6:7]
	v_pk_mul_f32 v[8:9], v[116:117], v[8:9]
	v_pk_add_f32 v[4:5], v[178:179], 1.0 op_sel_hi:[1,0]
	v_pk_add_f32 v[10:11], v[180:181], 1.0 op_sel_hi:[1,0]
	v_pk_fma_f32 v[6:7], v[4:5], v[6:7], v[146:147]
	v_pk_fma_f32 v[8:9], v[10:11], v[8:9], v[148:149]
	v_cvt_pk_bf16_f32 v12, v6, v7
	v_cvt_pk_bf16_f32 v13, v8, v9
	global_store_dwordx2 v81, v[12:13], s[100:101] offset:2560
	v_pk_mul_f32 v[82:83], v[118:119], v[82:83]
	v_pk_mul_f32 v[84:85], v[120:121], v[84:85]
	v_pk_add_f32 v[4:5], v[182:183], 1.0 op_sel_hi:[1,0]
	v_pk_add_f32 v[10:11], v[184:185], 1.0 op_sel_hi:[1,0]
	v_pk_fma_f32 v[82:83], v[4:5], v[82:83], v[150:151]
	v_pk_fma_f32 v[84:85], v[10:11], v[84:85], v[152:153]
	v_cvt_pk_bf16_f32 v12, v82, v83
	v_cvt_pk_bf16_f32 v13, v84, v85
	global_store_dwordx2 v81, v[12:13], s[100:101] offset:3072
	v_pk_mul_f32 v[86:87], v[122:123], v[86:87]
	v_pk_mul_f32 v[88:89], v[124:125], v[88:89]
	v_pk_add_f32 v[4:5], v[186:187], 1.0 op_sel_hi:[1,0]
	v_pk_add_f32 v[10:11], v[188:189], 1.0 op_sel_hi:[1,0]
	v_pk_fma_f32 v[86:87], v[4:5], v[86:87], v[154:155]
	v_pk_fma_f32 v[88:89], v[10:11], v[88:89], v[156:157]
	v_cvt_pk_bf16_f32 v12, v86, v87
	v_cvt_pk_bf16_f32 v13, v88, v89
	global_store_dwordx2 v81, v[12:13], s[100:101] offset:3584
	s_mov_b32 s4, s32
	s_cmp_lt_u32 s4, s83
	s_cbranch_scc1 .Lnorm_loop
	s_branch .LBB0_86
